# L1 invalidate issued before the poll (overlapping its round trip) in the P0|P1 and P1|P2 seams, as the baseline's team barrier does
# speedup vs baseline: 1.0001x; 1.0001x over previous
; __device__ __forceinline__ unsigned xb_ld(unsigned* p)              { return __hip_atomic_load(p, __ATOMIC_RELAXED, __HIP_MEMORY_SCOPE_AGENT); }
; __device__ __forceinline__ unsigned xb_add(unsigned* p, unsigned v) { return __hip_atomic_fetch_add(p, v, __ATOMIC_RELAXED, __HIP_MEMORY_SCOPE_AGENT); }
; #define XB_SPIN(cond, bar) do { unsigned _sp = 0; while (cond) { __builtin_amdgcn_s_sleep(1); \
;     if ((++_sp & 255u) == 0u) { if (xb_ld(&(bar)[XB_TMO])) break; if (_sp > XB_SPIN_CAP) { atomicAdd(&(bar)[XB_TMO], 1u); break; } } } } while (0)
; __device__ __forceinline__ void team_barrier(unsigned* ctr, unsigned target, unsigned* bar) {
;     asm volatile("s_waitcnt vmcnt(0)" ::: "memory");
;     __syncthreads();
;     if (threadIdx.x == 0) {
;         __builtin_amdgcn_s_waitcnt(0);
;         (void)xb_add(ctr, 1u);
;         asm volatile("buffer_inv sc1" ::: "memory");
;         XB_SPIN(xb_ld(ctr) < target, bar);
;         asm volatile("s_waitcnt vmcnt(0)" ::: "memory");
;     }
;     __syncthreads();
; }
.LBB0_65:
	s_cmp_gt_i32 s57, 1
	s_barrier
	s_cbranch_scc0 .LBB0_115
	s_waitcnt vmcnt(0)
	s_barrier
	s_and_saveexec_b64 s[6:7], s[96:97]
	s_cbranch_execz .Lts0_join
	s_and_b32 s3, s2, 7
	s_lshl_b32 s3, s3, 3
	s_bfe_u32 s4, s2, 0x30003
	s_or_b32 s3, s3, s4
	s_lshl_b32 s3, s3, 7
	s_add_u32 s8, s60, s3
	s_addc_u32 s9, s61, 0
	s_add_u32 s8, s8, 0x2d000
	s_addc_u32 s9, s9, 0
	v_mov_b32_e32 v1, 0
	v_mov_b32_e32 v2, 1
	v_mov_b32_e32 v3, 0x2c100
	v_mov_b32_e32 v5, 0
	global_atomic_add v1, v2, s[8:9]
	buffer_inv sc1
.Lts0_spin:
	global_load_dword v6, v1, s[8:9] sc1
	global_load_dword v7, v3, s[60:61] sc1
	s_waitcnt vmcnt(0)
	v_lshrrev_b32_e32 v6, 2, v6
	v_lshrrev_b32_e32 v7, 8, v7
	v_min_u32_e32 v6, v6, v7
	v_cmp_ne_u32_e32 vcc, 0, v6
	s_cbranch_vccnz .Lts0_done
	s_sleep 1
	v_add_u32_e32 v5, 1, v5
	v_cmp_gt_u32_e32 vcc, 0x4000, v5
	s_cbranch_vccnz .Lts0_spin
	global_atomic_add v1, v2, s[58:59] offset:512
.Lts0_done:
	s_waitcnt vmcnt(0)

; __device__ __forceinline__ unsigned xb_ld(unsigned* p)              { return __hip_atomic_load(p, __ATOMIC_RELAXED, __HIP_MEMORY_SCOPE_AGENT); }
; __device__ __forceinline__ unsigned xb_add(unsigned* p, unsigned v) { return __hip_atomic_fetch_add(p, v, __ATOMIC_RELAXED, __HIP_MEMORY_SCOPE_AGENT); }
; #define XB_SPIN(cond, bar) do { unsigned _sp = 0; while (cond) { __builtin_amdgcn_s_sleep(1); \
;     if ((++_sp & 255u) == 0u) { if (xb_ld(&(bar)[XB_TMO])) break; if (_sp > XB_SPIN_CAP) { atomicAdd(&(bar)[XB_TMO], 1u); break; } } } } while (0)
; __device__ __forceinline__ void team_barrier(unsigned* ctr, unsigned target, unsigned* bar) {
;     asm volatile("s_waitcnt vmcnt(0)" ::: "memory");
;     __syncthreads();
;     if (threadIdx.x == 0) {
;         __builtin_amdgcn_s_waitcnt(0);
;         (void)xb_add(ctr, 1u);
;         asm volatile("buffer_inv sc1" ::: "memory");
;         XB_SPIN(xb_ld(ctr) < target, bar);
;         asm volatile("s_waitcnt vmcnt(0)" ::: "memory");
;     }
;     __syncthreads();
; }
.Lts1_nowb:
	s_lshl_b32 s3, s4, 7
	s_add_u32 s8, s60, s3
	s_addc_u32 s9, s61, 0
	s_add_u32 s8, s8, 0x2a000
	s_addc_u32 s9, s9, 0
	s_add_i32 s3, s4, -1
	s_max_i32 s3, s3, 0
	s_lshl_b32 s3, s3, 7
	s_add_u32 s10, s60, s3
	s_addc_u32 s11, s61, 0
	s_add_u32 s10, s10, 0x2a000
	s_addc_u32 s11, s11, 0
	v_mov_b32_e32 v1, 0
	v_mov_b32_e32 v2, 1
	v_mov_b32_e32 v3, 0x2c000
	v_mov_b32_e32 v5, 0
	global_atomic_add v1, v2, s[8:9]
	global_atomic_add v3, v2, s[60:61]
	buffer_inv sc1
.Lts1_spin:
	global_load_dword v6, v1, s[8:9] sc1
	global_load_dword v7, v1, s[10:11] sc1
	s_waitcnt vmcnt(0)
	v_min_u32_e32 v6, v6, v7
	v_cmp_lt_u32_e32 vcc, 3, v6
	s_cbranch_vccnz .Lts1_done
	s_sleep 1
	v_add_u32_e32 v5, 1, v5
	v_cmp_gt_u32_e32 vcc, 0x4000, v5
	s_cbranch_vccnz .Lts1_spin
	global_atomic_add v1, v2, s[58:59] offset:512
.Lts1_done:
	s_waitcnt vmcnt(0)
